# sc1 (write-through, no dirty L2 line) on the 8 ACT stores of the GEMM3 epilogue only
# speedup vs baseline: 1.0011x; 1.0011x over previous
; __device__ __forceinline__ size_t act_off(int r, int j) { return ((size_t)((r >> 8) * (DFF / 64) + (j >> 6)) * 256 + (r & 255)) * 64 + (j & 63); }
;     __device__ __forceinline__ void operator()(const f32x4 (&acc)[2][2][4][2], const Unit& u, int wr, int wc, int fr, int fq) const {
;     ...
;                     const int r = u.pm * BM + ai * HALF + wr * 64 + m * 16 + fr;
;                     const float rsm = RS[16 * m]; const f32x4 g = acc[ai][0][m][n] * rsm, uu = acc[ai][1][m][n] * rsm; f32x4 p1, p2, av;
;                     if (!sample) {
; #pragma unroll
;                         for (int e = 0; e < 4; ++e) { float o1, o2;
;                             if (m == 0) { o1 = bm1[e]; o2 = (fr == 0) ? bm2[e] : bm1[e]; } else { const float gp = acc[ai][0][m > 0 ? m - 1 : 0][n][e] * RS[16 * (m > 0 ? m - 1 : 0)]; o1 = dpp_ror1(gp); o2 = dpp_ror2(gp); }
;                             p1[e] = dpp_shr1(o1, g[e]); p2[e] = dpp_shr2(o2, g[e]); }
;                         if (ai == 0 && wr == 0 && m == 0 && fr < 2 && (u.pm & 7) != 0) {
;                             *(f32x4*)(fix + ((size_t)(72 + u.pm * 2 + fr)) * DFF + j0 + 4 * n) = g; *(f32x4*)(fix + ((size_t)(144 + u.pm * 2 + fr)) * DFF + j0 + 4 * n) = uu; }
;                     } else {
;                         const int t = fr & 7, bs = (r - MP) >> 3; f32x4 s0 = (f32x4){0.f, 0.f, 0.f, 0.f}, s1 = s0;
;                         if (t < 2) { s0 = *(const f32x4*)(st_ffn + ((size_t)bs * 2 + 0) * DFF + j0 + 4 * n); s1 = *(const f32x4*)(st_ffn + ((size_t)bs * 2 + 1) * DFF + j0 + 4 * n); }
; #pragma unroll
;                         for (int e = 0; e < 4; ++e) { const float a1 = dpp_shr1(0.f, g[e]), a2 = dpp_shr2(0.f, g[e]); p1[e] = (t >= 1) ? a1 : s1[e]; p2[e] = (t >= 2) ? a2 : (t == 1 ? s1[e] : s0[e]); }
;                         if (t >= 6) *(f32x4*)(out + O_SFFN + ((size_t)bs * 2 + (t - 6)) * DFF + j0 + 4 * n) = g;
;                     }
;                     const f32x4 gc = bb + w0 * p2 + w1 * p1 + w2 * g;
; #pragma unroll
;                     for (int e = 0; e < 4; ++e) av[e] = silu_e(gc[e]) * uu[e];
;                     if (n == 0) { keep[ai][m].x = cvt_pk_bf16(av[0], av[1]); keep[ai][m].y = cvt_pk_bf16(av[2], av[3]); }
;                     else { u32x4e w; w.x = keep[ai][m].x; w.y = keep[ai][m].y; w.z = cvt_pk_bf16(av[0], av[1]); w.w = cvt_pk_bf16(av[2], av[3]); *(u32x4e*)(ACT + act_off(r, j0)) = w; }
.LBB0_832:
	s_or_b64 exec, exec, s[20:21]
	s_and_saveexec_b64 s[20:21], s[78:79]
	v_mov_b64_e32 v[124:125], v[4:5]
	v_mov_b64_e32 v[122:123], v[2:3]
	v_mov_b32_e32 v96, v212
	v_mov_b32_e32 v97, v213
	v_mov_b32_e32 v100, v214
	v_mov_b32_e32 v101, v215
	s_or_b64 exec, exec, s[20:21]
	v_mov_b32_e32 v80, v89
	v_mov_b32_e32 v81, v95
	v_mov_b32_e32 v108, v107
	v_mov_b32_e32 v109, v125
	v_pk_mul_f32 v[108:109], v[80:81], v[108:109]
	v_fma_f32 v84, v75, v101, v79
	v_add_f32_e32 v84, v109, v84
	v_add_f32_e32 v84, v108, v84
	v_mul_f32_e32 v89, 0xbfb8aa3b, v84
	v_exp_f32_e32 v89, v89
	v_mov_b32_e32 v107, v124
	v_fma_f32 v100, v74, v100, v78
	v_mov_b32_e32 v108, v87
	v_add_f32_e32 v89, 1.0, v89
	v_rcp_f32_e32 v101, v89
	v_mov_b32_e32 v89, v94
	v_pk_mul_f32 v[94:95], v[88:89], v[106:107]
	v_mov_b32_e32 v109, v93
	v_add_f32_e32 v95, v95, v100
	v_add_f32_e32 v100, v94, v95
	v_mul_f32_e32 v94, 0xbfb8aa3b, v100
	v_exp_f32_e32 v94, v94
	v_mul_f32_e32 v84, v84, v101
	v_mul_f32_e32 v69, v69, v84
	v_mov_b32_e32 v95, v123
	v_add_f32_e32 v84, 1.0, v94
	v_mov_b32_e32 v94, v105
	v_pk_mul_f32 v[94:95], v[108:109], v[94:95]
	v_fma_f32 v87, v73, v97, v77
	v_add_f32_e32 v87, v95, v87
	v_add_f32_e32 v94, v94, v87
	v_mul_f32_e32 v87, 0xbfb8aa3b, v94
	v_exp_f32_e32 v95, v87
	v_mov_b32_e32 v87, v92
	v_mov_b32_e32 v105, v122
	v_pk_mul_f32 v[92:93], v[86:87], v[104:105]
	v_fma_f32 v96, v72, v96, v76
	v_add_f32_e32 v93, v93, v96
	v_add_f32_e32 v92, v92, v93
	v_mul_f32_e32 v93, 0xbfb8aa3b, v92
	v_exp_f32_e32 v93, v93
	v_rcp_f32_e32 v84, v84
	v_add_f32_e32 v95, 1.0, v95
	v_rcp_f32_e32 v95, v95
	v_add_f32_e32 v93, 1.0, v93
	v_rcp_f32_e32 v93, v93
	v_mul_f32_e32 v84, v100, v84
	v_mul_f32_e32 v68, v68, v84
	v_mul_f32_e32 v84, v94, v95
	v_mul_f32_e32 v67, v67, v84
	v_mul_f32_e32 v84, v92, v93
	v_mul_f32_e32 v66, v66, v84
	v_ashrrev_i32_e32 v125, 6, v184
	v_cvt_pk_bf16_f32 v122, v66, v67
	v_lshrrev_b32_e32 v66, 8, v85
	v_mad_i32_i24 v66, v66, s60, v125
	v_cvt_pk_bf16_f32 v123, v68, v69
	v_ashrrev_i32_e32 v67, 31, v66
	ds_read_b32 v84, v187 offset:64
	v_lshlrev_b64 v[66:67], 15, v[66:67]
	v_lshlrev_b32_e32 v68, 7, v217
	v_and_b32_e32 v106, 56, v216
	v_lshl_add_u64 v[66:67], s[40:41], 0, v[66:67]
	v_and_b32_e32 v68, 0x7f80, v68
	v_mov_b32_e32 v69, v179
	v_lshl_add_u64 v[66:67], v[66:67], 0, v[68:69]
	v_lshlrev_b32_e32 v110, 1, v106
	v_mov_b32_e32 v111, v179
	v_lshl_add_u64 v[66:67], v[66:67], 0, v[110:111]
	global_store_dwordx4 v[66:67], v[120:123], off sc1
	v_add_u32_e32 v100, s74, v164
	s_waitcnt lgkmcnt(0)
	v_pk_mul_f32 v[68:69], v[56:57], v[84:85] op_sel_hi:[1,0]
	v_pk_mul_f32 v[66:67], v[54:55], v[84:85] op_sel_hi:[1,0]
	s_and_b64 vcc, exec, s[16:17]
	s_mov_b64 s[20:21], -1
	s_cbranch_vccnz .LBB0_840
	v_add_u32_e32 v85, 0xffffe000, v100
	v_ashrrev_i32_e32 v92, 3, v85
	v_mov_b32_e32 v94, 0
	v_mov_b32_e32 v95, 0
	v_mov_b32_e32 v96, 0
	v_mov_b32_e32 v97, 0
	v_mov_b32_e32 v104, 0
	v_mov_b32_e32 v105, 0
	v_mov_b32_e32 v106, 0
	v_mov_b32_e32 v107, 0
	s_and_saveexec_b64 s[20:21], s[14:15]
	s_cbranch_execz .LBB0_837
	v_mov_b64_e32 v[94:95], s[36:37]
	v_mad_i64_i32 v[94:95], s[76:77], v92, s53, v[94:95]
	v_lshl_add_u64 v[94:95], v[184:185], 2, v[94:95]
	v_add_co_u32_e32 v104, vcc, 0xa000, v94
	s_nop 1
	v_addc_co_u32_e32 v105, vcc, 0, v95, vcc
	global_load_dwordx4 v[94:97], v[94:95], off offset:16
	s_nop 0
	global_load_dwordx4 v[104:107], v[104:105], off offset:3088

; __device__ __forceinline__ size_t act_off(int r, int j) { return ((size_t)((r >> 8) * (DFF / 64) + (j >> 6)) * 256 + (r & 255)) * 64 + (j & 63); }
;     __device__ __forceinline__ void operator()(const f32x4 (&acc)[2][2][4][2], const Unit& u, int wr, int wc, int fr, int fq) const {
;     ...
;                     const int r = u.pm * BM + ai * HALF + wr * 64 + m * 16 + fr;
;                     const float rsm = RS[16 * m]; const f32x4 g = acc[ai][0][m][n] * rsm, uu = acc[ai][1][m][n] * rsm; f32x4 p1, p2, av;
;                     if (!sample) {
; #pragma unroll
;                         for (int e = 0; e < 4; ++e) { float o1, o2;
;                             if (m == 0) { o1 = bm1[e]; o2 = (fr == 0) ? bm2[e] : bm1[e]; } else { const float gp = acc[ai][0][m > 0 ? m - 1 : 0][n][e] * RS[16 * (m > 0 ? m - 1 : 0)]; o1 = dpp_ror1(gp); o2 = dpp_ror2(gp); }
;                             p1[e] = dpp_shr1(o1, g[e]); p2[e] = dpp_shr2(o2, g[e]); }
;                         if (ai == 0 && wr == 0 && m == 0 && fr < 2 && (u.pm & 7) != 0) {
;                             *(f32x4*)(fix + ((size_t)(72 + u.pm * 2 + fr)) * DFF + j0 + 4 * n) = g; *(f32x4*)(fix + ((size_t)(144 + u.pm * 2 + fr)) * DFF + j0 + 4 * n) = uu; }
;                     } else {
;                         const int t = fr & 7, bs = (r - MP) >> 3; f32x4 s0 = (f32x4){0.f, 0.f, 0.f, 0.f}, s1 = s0;
;                         if (t < 2) { s0 = *(const f32x4*)(st_ffn + ((size_t)bs * 2 + 0) * DFF + j0 + 4 * n); s1 = *(const f32x4*)(st_ffn + ((size_t)bs * 2 + 1) * DFF + j0 + 4 * n); }
; #pragma unroll
;                         for (int e = 0; e < 4; ++e) { const float a1 = dpp_shr1(0.f, g[e]), a2 = dpp_shr2(0.f, g[e]); p1[e] = (t >= 1) ? a1 : s1[e]; p2[e] = (t >= 2) ? a2 : (t == 1 ? s1[e] : s0[e]); }
;                         if (t >= 6) *(f32x4*)(out + O_SFFN + ((size_t)bs * 2 + (t - 6)) * DFF + j0 + 4 * n) = g;
;                     }
;                     const f32x4 gc = bb + w0 * p2 + w1 * p1 + w2 * g;
; #pragma unroll
;                     for (int e = 0; e < 4; ++e) av[e] = silu_e(gc[e]) * uu[e];
;                     if (n == 0) { keep[ai][m].x = cvt_pk_bf16(av[0], av[1]); keep[ai][m].y = cvt_pk_bf16(av[2], av[3]); }
;                     else { u32x4e w; w.x = keep[ai][m].x; w.y = keep[ai][m].y; w.z = cvt_pk_bf16(av[0], av[1]); w.w = cvt_pk_bf16(av[2], av[3]); *(u32x4e*)(ACT + act_off(r, j0)) = w; }
.LBB0_842:
	v_mov_b32_e32 v62, v69
	v_mov_b32_e32 v63, v95
	v_pk_mul_f32 v[62:63], v[80:81], v[62:63]
	v_fma_f32 v64, v75, v97, v79
	v_add_f32_e32 v63, v63, v64
	v_add_f32_e32 v64, v62, v63
	v_mul_f32_e32 v62, 0xbfb8aa3b, v64
	v_exp_f32_e32 v65, v62
	v_mov_b32_e32 v62, v84
	v_mov_b32_e32 v63, v84
	v_pk_mul_f32 v[60:61], v[60:61], v[62:63]
	v_add_f32_e32 v62, 1.0, v65
	v_mov_b32_e32 v69, v94
	v_rcp_f32_e32 v65, v62
	v_pk_mul_f32 v[62:63], v[88:89], v[68:69]
	v_fma_f32 v68, v74, v96, v78
	v_add_f32_e32 v63, v63, v68
	v_add_f32_e32 v68, v62, v63
	v_mul_f32_e32 v62, 0xbfb8aa3b, v68
	v_exp_f32_e32 v62, v62
	v_mul_f32_e32 v63, v64, v65
	v_mul_f32_e32 v61, v61, v63
	v_mov_b32_e32 v63, v93
	v_add_f32_e32 v62, 1.0, v62
	v_rcp_f32_e32 v64, v62
	v_mov_b32_e32 v62, v67
	v_pk_mul_f32 v[62:63], v[108:109], v[62:63]
	v_fma_f32 v65, v73, v104, v77
	v_add_f32_e32 v63, v63, v65
	v_add_f32_e32 v65, v62, v63
	v_mul_f32_e32 v62, 0xbfb8aa3b, v65
	v_mov_b32_e32 v67, v92
	v_exp_f32_e32 v69, v62
	v_pk_mul_f32 v[62:63], v[86:87], v[66:67]
	v_fma_f32 v66, v72, v101, v76
	v_add_f32_e32 v63, v63, v66
	v_add_f32_e32 v62, v62, v63
	v_mul_f32_e32 v63, 0xbfb8aa3b, v62
	v_exp_f32_e32 v63, v63
	v_add_f32_e32 v66, 1.0, v69
	v_rcp_f32_e32 v66, v66
	v_mov_b32_e32 v85, v84
	v_add_f32_e32 v63, 1.0, v63
	v_rcp_f32_e32 v63, v63
	v_pk_mul_f32 v[58:59], v[58:59], v[84:85]
	v_mul_f32_e32 v64, v68, v64
	v_mul_f32_e32 v60, v60, v64
	v_mul_f32_e32 v62, v62, v63
	v_mul_f32_e32 v64, v65, v66
	v_mul_f32_e32 v58, v58, v62
	v_mul_f32_e32 v59, v59, v64
	v_cvt_pk_bf16_f32 v120, v58, v59
	v_lshrrev_b32_e32 v58, 8, v100
	v_mad_i32_i24 v58, v58, s60, v125
	v_cvt_pk_bf16_f32 v121, v60, v61
	v_ashrrev_i32_e32 v59, 31, v58
	ds_read_b32 v68, v187 offset:128
	v_lshlrev_b64 v[58:59], 15, v[58:59]
	v_lshlrev_b32_e32 v60, 7, v164
	v_lshl_add_u64 v[58:59], s[40:41], 0, v[58:59]
	v_and_b32_e32 v60, 0x7f80, v60
	v_mov_b32_e32 v61, v179
	v_lshl_add_u64 v[58:59], v[58:59], 0, v[60:61]
	v_mov_b32_e32 v111, v179
	v_lshl_add_u64 v[58:59], v[58:59], 0, v[110:111]
	global_store_dwordx4 v[58:59], v[118:121], off sc1
	v_add_u32_e32 v84, s74, v158
	s_waitcnt lgkmcnt(0)
	v_pk_mul_f32 v[60:61], v[44:45], v[68:69] op_sel_hi:[1,0]
	v_pk_mul_f32 v[58:59], v[42:43], v[68:69] op_sel_hi:[1,0]
	s_and_b64 vcc, exec, s[16:17]
	s_mov_b64 s[20:21], -1
	s_cbranch_vccnz .LBB0_848
	v_add_u32_e32 v62, 0xffffe000, v84
	v_ashrrev_i32_e32 v62, 3, v62
	v_mov_b32_e32 v64, 0
	v_mov_b32_e32 v65, 0
	v_mov_b32_e32 v66, 0
	v_mov_b32_e32 v67, 0
	v_mov_b32_e32 v92, 0
	v_mov_b32_e32 v93, 0
	v_mov_b32_e32 v94, 0
	v_mov_b32_e32 v95, 0
	s_and_saveexec_b64 s[20:21], s[14:15]
	s_cbranch_execz .LBB0_845
	v_mov_b64_e32 v[64:65], s[36:37]
	v_mad_i64_i32 v[64:65], s[76:77], v62, s53, v[64:65]
	v_lshl_add_u64 v[64:65], v[184:185], 2, v[64:65]
	v_add_co_u32_e32 v92, vcc, 0xa000, v64
	s_nop 1
	v_addc_co_u32_e32 v93, vcc, 0, v65, vcc
	global_load_dwordx4 v[64:67], v[64:65], off offset:16
	s_nop 0
	global_load_dwordx4 v[92:95], v[92:93], off offset:3088

; __device__ __forceinline__ size_t act_off(int r, int j) { return ((size_t)((r >> 8) * (DFF / 64) + (j >> 6)) * 256 + (r & 255)) * 64 + (j & 63); }
;     __device__ __forceinline__ void operator()(const f32x4 (&acc)[2][2][4][2], const Unit& u, int wr, int wc, int fr, int fq) const {
;     ...
;                     const int r = u.pm * BM + ai * HALF + wr * 64 + m * 16 + fr;
;                     const float rsm = RS[16 * m]; const f32x4 g = acc[ai][0][m][n] * rsm, uu = acc[ai][1][m][n] * rsm; f32x4 p1, p2, av;
;                     if (!sample) {
; #pragma unroll
;                         for (int e = 0; e < 4; ++e) { float o1, o2;
;                             if (m == 0) { o1 = bm1[e]; o2 = (fr == 0) ? bm2[e] : bm1[e]; } else { const float gp = acc[ai][0][m > 0 ? m - 1 : 0][n][e] * RS[16 * (m > 0 ? m - 1 : 0)]; o1 = dpp_ror1(gp); o2 = dpp_ror2(gp); }
;                             p1[e] = dpp_shr1(o1, g[e]); p2[e] = dpp_shr2(o2, g[e]); }
;                         if (ai == 0 && wr == 0 && m == 0 && fr < 2 && (u.pm & 7) != 0) {
;                             *(f32x4*)(fix + ((size_t)(72 + u.pm * 2 + fr)) * DFF + j0 + 4 * n) = g; *(f32x4*)(fix + ((size_t)(144 + u.pm * 2 + fr)) * DFF + j0 + 4 * n) = uu; }
;                     } else {
;                         const int t = fr & 7, bs = (r - MP) >> 3; f32x4 s0 = (f32x4){0.f, 0.f, 0.f, 0.f}, s1 = s0;
;                         if (t < 2) { s0 = *(const f32x4*)(st_ffn + ((size_t)bs * 2 + 0) * DFF + j0 + 4 * n); s1 = *(const f32x4*)(st_ffn + ((size_t)bs * 2 + 1) * DFF + j0 + 4 * n); }
; #pragma unroll
;                         for (int e = 0; e < 4; ++e) { const float a1 = dpp_shr1(0.f, g[e]), a2 = dpp_shr2(0.f, g[e]); p1[e] = (t >= 1) ? a1 : s1[e]; p2[e] = (t >= 2) ? a2 : (t == 1 ? s1[e] : s0[e]); }
;                         if (t >= 6) *(f32x4*)(out + O_SFFN + ((size_t)bs * 2 + (t - 6)) * DFF + j0 + 4 * n) = g;
;                     }
;                     const f32x4 gc = bb + w0 * p2 + w1 * p1 + w2 * g;
; #pragma unroll
;                     for (int e = 0; e < 4; ++e) av[e] = silu_e(gc[e]) * uu[e];
;                     if (n == 0) { keep[ai][m].x = cvt_pk_bf16(av[0], av[1]); keep[ai][m].y = cvt_pk_bf16(av[2], av[3]); }
;                     else { u32x4e w; w.x = keep[ai][m].x; w.y = keep[ai][m].y; w.z = cvt_pk_bf16(av[0], av[1]); w.w = cvt_pk_bf16(av[2], av[3]); *(u32x4e*)(ACT + act_off(r, j0)) = w; }
.LBB0_850:
	v_mov_b32_e32 v54, v61
	v_mov_b32_e32 v55, v65
	v_pk_mul_f32 v[54:55], v[80:81], v[54:55]
	v_fma_f32 v56, v75, v67, v79
	v_add_f32_e32 v55, v55, v56
	v_add_f32_e32 v56, v54, v55
	v_mul_f32_e32 v54, 0xbfb8aa3b, v56
	v_exp_f32_e32 v57, v54
	v_mov_b32_e32 v54, v68
	v_mov_b32_e32 v55, v68
	v_pk_mul_f32 v[52:53], v[52:53], v[54:55]
	v_add_f32_e32 v54, 1.0, v57
	v_mov_b32_e32 v61, v64
	v_rcp_f32_e32 v57, v54
	v_pk_mul_f32 v[54:55], v[88:89], v[60:61]
	v_fma_f32 v60, v74, v66, v78
	v_add_f32_e32 v55, v55, v60
	v_add_f32_e32 v60, v54, v55
	v_mul_f32_e32 v54, 0xbfb8aa3b, v60
	v_exp_f32_e32 v54, v54
	v_mul_f32_e32 v55, v56, v57
	v_mul_f32_e32 v53, v53, v55
	v_mov_b32_e32 v55, v63
	v_add_f32_e32 v54, 1.0, v54
	v_rcp_f32_e32 v56, v54
	v_mov_b32_e32 v54, v59
	v_pk_mul_f32 v[54:55], v[108:109], v[54:55]
	v_fma_f32 v57, v73, v92, v77
	v_add_f32_e32 v55, v55, v57
	v_add_f32_e32 v57, v54, v55
	v_mul_f32_e32 v54, 0xbfb8aa3b, v57
	v_mov_b32_e32 v59, v62
	v_exp_f32_e32 v61, v54
	v_pk_mul_f32 v[54:55], v[86:87], v[58:59]
	v_fma_f32 v58, v72, v85, v76
	v_add_f32_e32 v55, v55, v58
	v_add_f32_e32 v54, v54, v55
	v_mul_f32_e32 v55, 0xbfb8aa3b, v54
	v_exp_f32_e32 v55, v55
	v_add_f32_e32 v58, 1.0, v61
	v_rcp_f32_e32 v58, v58
	v_mov_b32_e32 v69, v68
	v_add_f32_e32 v55, 1.0, v55
	v_rcp_f32_e32 v55, v55
	v_pk_mul_f32 v[50:51], v[50:51], v[68:69]
	v_mul_f32_e32 v56, v60, v56
	v_mul_f32_e32 v52, v52, v56
	v_mul_f32_e32 v54, v54, v55
	v_mul_f32_e32 v56, v57, v58
	v_mul_f32_e32 v50, v50, v54
	v_mul_f32_e32 v51, v51, v56
	v_cvt_pk_bf16_f32 v116, v50, v51
	v_lshrrev_b32_e32 v50, 8, v84
	v_cvt_pk_bf16_f32 v117, v52, v53
	v_mad_i32_i24 v50, v50, s60, v125
	ds_read_b32 v60, v187 offset:192
	v_ashrrev_i32_e32 v51, 31, v50
	v_lshlrev_b64 v[50:51], 15, v[50:51]
	v_lshlrev_b32_e32 v52, 7, v158
	v_lshl_add_u64 v[50:51], s[40:41], 0, v[50:51]
	v_and_b32_e32 v52, 0x7f80, v52
	v_mov_b32_e32 v53, v179
	v_lshl_add_u64 v[50:51], v[50:51], 0, v[52:53]
	v_mov_b32_e32 v111, v179
	v_lshl_add_u64 v[50:51], v[50:51], 0, v[110:111]
	v_add_u32_e32 v62, s74, v152
	s_waitcnt lgkmcnt(0)
	v_pk_mul_f32 v[48:49], v[48:49], v[60:61] op_sel_hi:[1,0]
	v_pk_mul_f32 v[46:47], v[46:47], v[60:61] op_sel_hi:[1,0]
	s_and_b64 vcc, exec, s[16:17]
	s_mov_b64 s[20:21], -1
	global_store_dwordx4 v[50:51], v[114:117], off sc1
	s_cbranch_vccnz .LBB0_856
	v_add_u32_e32 v50, 0xffffe000, v62
	v_ashrrev_i32_e32 v50, 3, v50
	v_mov_b32_e32 v52, 0
	v_mov_b32_e32 v53, 0
	v_mov_b32_e32 v54, 0
	v_mov_b32_e32 v55, 0
	v_mov_b32_e32 v56, 0
	v_mov_b32_e32 v57, 0
	v_mov_b32_e32 v58, 0
	v_mov_b32_e32 v59, 0
	s_and_saveexec_b64 s[20:21], s[14:15]
	s_cbranch_execz .LBB0_853
	v_mov_b64_e32 v[52:53], s[36:37]
	v_mad_i64_i32 v[52:53], s[76:77], v50, s53, v[52:53]
	v_lshl_add_u64 v[52:53], v[184:185], 2, v[52:53]
	v_add_co_u32_e32 v56, vcc, 0xa000, v52
	s_nop 1
	v_addc_co_u32_e32 v57, vcc, 0, v53, vcc
	global_load_dwordx4 v[52:55], v[52:53], off offset:16
	s_nop 0
	global_load_dwordx4 v[56:59], v[56:57], off offset:3088

;     __device__ __forceinline__ void operator()(const f32x4 (&acc)[2][2][4][2], const Unit& u, int wr, int wc, int fr, int fq) const {
;     ...
;                 if (!sample && (wr == 1 || ai == 1)) { const int sa = (wr == 1) ? ai : 0, sw = (wr == 1) ? 0 : 1;
;     ...
;                     const int r = u.pm * BM + ai * HALF + wr * 64 + m * 16 + fr;
;                     const float rsm = RS[16 * m]; const f32x4 g = acc[ai][0][m][n] * rsm, uu = acc[ai][1][m][n] * rsm; f32x4 p1, p2, av;
;                     if (!sample) {
; #pragma unroll
;                         for (int e = 0; e < 4; ++e) { float o1, o2;
;                             if (m == 0) { o1 = bm1[e]; o2 = (fr == 0) ? bm2[e] : bm1[e]; } else { const float gp = acc[ai][0][m > 0 ? m - 1 : 0][n][e] * RS[16 * (m > 0 ? m - 1 : 0)]; o1 = dpp_ror1(gp); o2 = dpp_ror2(gp); }
;                             p1[e] = dpp_shr1(o1, g[e]); p2[e] = dpp_shr2(o2, g[e]); }
;                         if (ai == 0 && wr == 0 && m == 0 && fr < 2 && (u.pm & 7) != 0) {
;                             *(f32x4*)(fix + ((size_t)(72 + u.pm * 2 + fr)) * DFF + j0 + 4 * n) = g; *(f32x4*)(fix + ((size_t)(144 + u.pm * 2 + fr)) * DFF + j0 + 4 * n) = uu; }
;                     } else {
;                         const int t = fr & 7, bs = (r - MP) >> 3; f32x4 s0 = (f32x4){0.f, 0.f, 0.f, 0.f}, s1 = s0;
;                         if (t < 2) { s0 = *(const f32x4*)(st_ffn + ((size_t)bs * 2 + 0) * DFF + j0 + 4 * n); s1 = *(const f32x4*)(st_ffn + ((size_t)bs * 2 + 1) * DFF + j0 + 4 * n); }
; #pragma unroll
;                         for (int e = 0; e < 4; ++e) { const float a1 = dpp_shr1(0.f, g[e]), a2 = dpp_shr2(0.f, g[e]); p1[e] = (t >= 1) ? a1 : s1[e]; p2[e] = (t >= 2) ? a2 : (t == 1 ? s1[e] : s0[e]); }
;                         if (t >= 6) *(f32x4*)(out + O_SFFN + ((size_t)bs * 2 + (t - 6)) * DFF + j0 + 4 * n) = g;
;                     }
;                     const f32x4 gc = bb + w0 * p2 + w1 * p1 + w2 * g;
; #pragma unroll
;                     for (int e = 0; e < 4; ++e) av[e] = silu_e(gc[e]) * uu[e];
;                     if (n == 0) { keep[ai][m].x = cvt_pk_bf16(av[0], av[1]); keep[ai][m].y = cvt_pk_bf16(av[2], av[3]); }
;                     else { u32x4e w; w.x = keep[ai][m].x; w.y = keep[ai][m].y; w.z = cvt_pk_bf16(av[0], av[1]); w.w = cvt_pk_bf16(av[2], av[3]); *(u32x4e*)(ACT + act_off(r, j0)) = w; }
.LBB0_858:
	v_mov_b32_e32 v42, v49
	v_mov_b32_e32 v43, v53
	v_pk_mul_f32 v[42:43], v[80:81], v[42:43]
	v_fma_f32 v44, v75, v55, v79
	v_add_f32_e32 v43, v43, v44
	v_add_f32_e32 v44, v42, v43
	v_mul_f32_e32 v42, 0xbfb8aa3b, v44
	v_exp_f32_e32 v45, v42
	v_mov_b32_e32 v42, v60
	v_mov_b32_e32 v43, v60
	v_pk_mul_f32 v[40:41], v[40:41], v[42:43]
	v_add_f32_e32 v42, 1.0, v45
	v_mov_b32_e32 v49, v52
	v_rcp_f32_e32 v45, v42
	v_pk_mul_f32 v[42:43], v[88:89], v[48:49]
	v_fma_f32 v48, v74, v54, v78
	v_add_f32_e32 v43, v43, v48
	v_add_f32_e32 v48, v42, v43
	v_mul_f32_e32 v42, 0xbfb8aa3b, v48
	v_exp_f32_e32 v42, v42
	v_mul_f32_e32 v43, v44, v45
	v_mul_f32_e32 v41, v41, v43
	v_mov_b32_e32 v43, v51
	v_add_f32_e32 v42, 1.0, v42
	v_rcp_f32_e32 v44, v42
	v_mov_b32_e32 v42, v47
	v_pk_mul_f32 v[42:43], v[108:109], v[42:43]
	v_fma_f32 v45, v73, v57, v77
	v_add_f32_e32 v43, v43, v45
	v_add_f32_e32 v45, v42, v43
	v_mul_f32_e32 v42, 0xbfb8aa3b, v45
	v_mov_b32_e32 v47, v50
	v_exp_f32_e32 v49, v42
	v_pk_mul_f32 v[42:43], v[86:87], v[46:47]
	v_fma_f32 v46, v72, v56, v76
	v_add_f32_e32 v43, v43, v46
	v_add_f32_e32 v42, v42, v43
	v_mul_f32_e32 v43, 0xbfb8aa3b, v42
	v_exp_f32_e32 v43, v43
	v_add_f32_e32 v46, 1.0, v49
	v_rcp_f32_e32 v46, v46
	v_mov_b32_e32 v61, v60
	v_add_f32_e32 v43, 1.0, v43
	v_rcp_f32_e32 v43, v43
	v_pk_mul_f32 v[38:39], v[38:39], v[60:61]
	v_mul_f32_e32 v44, v48, v44
	v_mul_f32_e32 v40, v40, v44
	v_mul_f32_e32 v42, v42, v43
	v_mul_f32_e32 v44, v45, v46
	v_mul_f32_e32 v38, v38, v42
	v_mul_f32_e32 v39, v39, v44
	v_cvt_pk_bf16_f32 v104, v38, v39
	v_lshrrev_b32_e32 v38, 8, v62
	v_mad_i32_i24 v38, v38, s60, v125
	v_ashrrev_i32_e32 v39, 31, v38
	v_cvt_pk_bf16_f32 v105, v40, v41
	v_lshlrev_b64 v[38:39], 15, v[38:39]
	v_lshlrev_b32_e32 v40, 7, v152
	v_lshl_add_u64 v[38:39], s[40:41], 0, v[38:39]
	v_and_b32_e32 v40, 0x7f80, v40
	v_mov_b32_e32 v41, v179
	v_lshl_add_u64 v[38:39], v[38:39], 0, v[40:41]
	v_mov_b32_e32 v111, v179
	v_lshl_add_u64 v[38:39], v[38:39], 0, v[110:111]
	v_mov_b32_e32 v46, 0
	s_and_b64 vcc, exec, s[22:23]
	v_mov_b32_e32 v47, 0
	v_mov_b32_e32 v48, 0
	v_mov_b32_e32 v49, 0
	v_mov_b32_e32 v42, 0
	v_mov_b32_e32 v43, 0
	v_mov_b32_e32 v44, 0
	v_mov_b32_e32 v45, 0
	global_store_dwordx4 v[38:39], v[102:105], off sc1
	s_cbranch_vccnz .LBB0_860
	ds_read_b128 v[46:49], v153 offset:16
	ds_read_b128 v[42:45], v153 offset:528

; __device__ __forceinline__ size_t act_off(int r, int j) { return ((size_t)((r >> 8) * (DFF / 64) + (j >> 6)) * 256 + (r & 255)) * 64 + (j & 63); }
;     __device__ __forceinline__ void operator()(const f32x4 (&acc)[2][2][4][2], const Unit& u, int wr, int wc, int fr, int fq) const {
;     ...
;                     const int r = u.pm * BM + ai * HALF + wr * 64 + m * 16 + fr;
;                     const float rsm = RS[16 * m]; const f32x4 g = acc[ai][0][m][n] * rsm, uu = acc[ai][1][m][n] * rsm; f32x4 p1, p2, av;
;                     if (!sample) {
; #pragma unroll
;                         for (int e = 0; e < 4; ++e) { float o1, o2;
;                             if (m == 0) { o1 = bm1[e]; o2 = (fr == 0) ? bm2[e] : bm1[e]; } else { const float gp = acc[ai][0][m > 0 ? m - 1 : 0][n][e] * RS[16 * (m > 0 ? m - 1 : 0)]; o1 = dpp_ror1(gp); o2 = dpp_ror2(gp); }
;                             p1[e] = dpp_shr1(o1, g[e]); p2[e] = dpp_shr2(o2, g[e]); }
;                         if (ai == 0 && wr == 0 && m == 0 && fr < 2 && (u.pm & 7) != 0) {
;                             *(f32x4*)(fix + ((size_t)(72 + u.pm * 2 + fr)) * DFF + j0 + 4 * n) = g; *(f32x4*)(fix + ((size_t)(144 + u.pm * 2 + fr)) * DFF + j0 + 4 * n) = uu; }
;                     } else {
;                         const int t = fr & 7, bs = (r - MP) >> 3; f32x4 s0 = (f32x4){0.f, 0.f, 0.f, 0.f}, s1 = s0;
;                         if (t < 2) { s0 = *(const f32x4*)(st_ffn + ((size_t)bs * 2 + 0) * DFF + j0 + 4 * n); s1 = *(const f32x4*)(st_ffn + ((size_t)bs * 2 + 1) * DFF + j0 + 4 * n); }
; #pragma unroll
;                         for (int e = 0; e < 4; ++e) { const float a1 = dpp_shr1(0.f, g[e]), a2 = dpp_shr2(0.f, g[e]); p1[e] = (t >= 1) ? a1 : s1[e]; p2[e] = (t >= 2) ? a2 : (t == 1 ? s1[e] : s0[e]); }
;                         if (t >= 6) *(f32x4*)(out + O_SFFN + ((size_t)bs * 2 + (t - 6)) * DFF + j0 + 4 * n) = g;
;                     }
;                     const f32x4 gc = bb + w0 * p2 + w1 * p1 + w2 * g;
; #pragma unroll
;                     for (int e = 0; e < 4; ++e) av[e] = silu_e(gc[e]) * uu[e];
;                     if (n == 0) { keep[ai][m].x = cvt_pk_bf16(av[0], av[1]); keep[ai][m].y = cvt_pk_bf16(av[2], av[3]); }
;                     else { u32x4e w; w.x = keep[ai][m].x; w.y = keep[ai][m].y; w.z = cvt_pk_bf16(av[0], av[1]); w.w = cvt_pk_bf16(av[2], av[3]); *(u32x4e*)(ACT + act_off(r, j0)) = w; }
.LBB0_868:
	v_mov_b32_e32 v42, v41
	v_mov_b32_e32 v43, v53
	v_pk_mul_f32 v[42:43], v[80:81], v[42:43]
	v_fma_f32 v41, v75, v55, v79
	v_add_f32_e32 v41, v43, v41
	v_add_f32_e32 v44, v42, v41
	v_mul_f32_e32 v41, 0xbfb8aa3b, v44
	v_exp_f32_e32 v41, v41
	v_mov_b32_e32 v42, v60
	v_mov_b32_e32 v43, v60
	v_pk_mul_f32 v[36:37], v[36:37], v[42:43]
	v_add_f32_e32 v41, 1.0, v41
	v_rcp_f32_e32 v42, v41
	v_mov_b32_e32 v41, v52
	v_pk_mul_f32 v[40:41], v[88:89], v[40:41]
	v_fma_f32 v43, v74, v54, v78
	v_add_f32_e32 v41, v41, v43
	v_add_f32_e32 v43, v40, v41
	v_mul_f32_e32 v40, 0xbfb8aa3b, v43
	v_exp_f32_e32 v40, v40
	v_mul_f32_e32 v41, v44, v42
	v_mul_f32_e32 v37, v37, v41
	v_mov_b32_e32 v41, v51
	v_add_f32_e32 v40, 1.0, v40
	v_rcp_f32_e32 v42, v40
	v_mov_b32_e32 v40, v39
	v_pk_mul_f32 v[40:41], v[108:109], v[40:41]
	v_fma_f32 v39, v73, v57, v77
	v_add_f32_e32 v39, v41, v39
	v_add_f32_e32 v40, v40, v39
	v_mul_f32_e32 v39, 0xbfb8aa3b, v40
	v_exp_f32_e32 v41, v39
	v_mov_b32_e32 v39, v50
	v_pk_mul_f32 v[38:39], v[86:87], v[38:39]
	v_fma_f32 v44, v72, v56, v76
	v_add_f32_e32 v39, v39, v44
	v_add_f32_e32 v38, v38, v39
	v_mul_f32_e32 v39, 0xbfb8aa3b, v38
	v_exp_f32_e32 v39, v39
	v_add_f32_e32 v41, 1.0, v41
	v_rcp_f32_e32 v41, v41
	v_mov_b32_e32 v61, v60
	v_add_f32_e32 v39, 1.0, v39
	v_rcp_f32_e32 v39, v39
	v_pk_mul_f32 v[34:35], v[34:35], v[60:61]
	v_mul_f32_e32 v40, v40, v41
	v_mul_f32_e32 v35, v35, v40
	v_mul_f32_e32 v38, v38, v39
	v_mul_f32_e32 v34, v34, v38
	v_cvt_pk_bf16_f32 v100, v34, v35
	v_lshrrev_b32_e32 v34, 8, v62
	v_mul_f32_e32 v42, v43, v42
	v_mad_i32_i24 v34, v34, s60, v125
	v_mul_f32_e32 v36, v36, v42
	v_cvt_pk_bf16_f32 v101, v36, v37
	v_ashrrev_i32_e32 v35, 31, v34
	ds_read_b32 v48, v150 offset:64
	v_lshlrev_b64 v[34:35], 15, v[34:35]
	v_lshlrev_b32_e32 v36, 7, v151
	v_lshl_add_u64 v[34:35], s[40:41], 0, v[34:35]
	v_and_b32_e32 v36, 0x7f80, v36
	v_mov_b32_e32 v37, v179
	v_lshl_add_u64 v[34:35], v[34:35], 0, v[36:37]
	v_mov_b32_e32 v111, v179
	v_lshl_add_u64 v[34:35], v[34:35], 0, v[110:111]
	global_store_dwordx4 v[34:35], v[98:101], off sc1
	v_add_u32_e32 v50, s74, v142
	s_waitcnt lgkmcnt(0)
	v_pk_mul_f32 v[36:37], v[24:25], v[48:49] op_sel_hi:[1,0]
	v_pk_mul_f32 v[34:35], v[22:23], v[48:49] op_sel_hi:[1,0]
	s_and_b64 vcc, exec, s[16:17]
	s_mov_b64 s[18:19], -1
	s_cbranch_vccnz .LBB0_874
	v_add_u32_e32 v38, 0xffffe000, v50
	v_ashrrev_i32_e32 v38, 3, v38
	v_mov_b32_e32 v40, 0
	v_mov_b32_e32 v41, 0
	v_mov_b32_e32 v42, 0
	v_mov_b32_e32 v43, 0
	v_mov_b32_e32 v44, 0
	v_mov_b32_e32 v45, 0
	v_mov_b32_e32 v46, 0
	v_mov_b32_e32 v47, 0
	s_and_saveexec_b64 s[18:19], s[14:15]
	s_cbranch_execz .LBB0_871
	v_mov_b64_e32 v[40:41], s[36:37]
	v_mad_i64_i32 v[40:41], s[20:21], v38, s53, v[40:41]
	v_lshl_add_u64 v[40:41], v[184:185], 2, v[40:41]
	v_add_co_u32_e32 v44, vcc, 0xa000, v40
	s_nop 1
	v_addc_co_u32_e32 v45, vcc, 0, v41, vcc
	global_load_dwordx4 v[40:43], v[40:41], off offset:16
	s_nop 0
	global_load_dwordx4 v[44:47], v[44:45], off offset:3088

; __device__ __forceinline__ size_t act_off(int r, int j) { return ((size_t)((r >> 8) * (DFF / 64) + (j >> 6)) * 256 + (r & 255)) * 64 + (j & 63); }
;     __device__ __forceinline__ void operator()(const f32x4 (&acc)[2][2][4][2], const Unit& u, int wr, int wc, int fr, int fq) const {
;     ...
;                     const int r = u.pm * BM + ai * HALF + wr * 64 + m * 16 + fr;
;                     const float rsm = RS[16 * m]; const f32x4 g = acc[ai][0][m][n] * rsm, uu = acc[ai][1][m][n] * rsm; f32x4 p1, p2, av;
;                     if (!sample) {
; #pragma unroll
;                         for (int e = 0; e < 4; ++e) { float o1, o2;
;                             if (m == 0) { o1 = bm1[e]; o2 = (fr == 0) ? bm2[e] : bm1[e]; } else { const float gp = acc[ai][0][m > 0 ? m - 1 : 0][n][e] * RS[16 * (m > 0 ? m - 1 : 0)]; o1 = dpp_ror1(gp); o2 = dpp_ror2(gp); }
;                             p1[e] = dpp_shr1(o1, g[e]); p2[e] = dpp_shr2(o2, g[e]); }
;                         if (ai == 0 && wr == 0 && m == 0 && fr < 2 && (u.pm & 7) != 0) {
;                             *(f32x4*)(fix + ((size_t)(72 + u.pm * 2 + fr)) * DFF + j0 + 4 * n) = g; *(f32x4*)(fix + ((size_t)(144 + u.pm * 2 + fr)) * DFF + j0 + 4 * n) = uu; }
;                     } else {
;                         const int t = fr & 7, bs = (r - MP) >> 3; f32x4 s0 = (f32x4){0.f, 0.f, 0.f, 0.f}, s1 = s0;
;                         if (t < 2) { s0 = *(const f32x4*)(st_ffn + ((size_t)bs * 2 + 0) * DFF + j0 + 4 * n); s1 = *(const f32x4*)(st_ffn + ((size_t)bs * 2 + 1) * DFF + j0 + 4 * n); }
; #pragma unroll
;                         for (int e = 0; e < 4; ++e) { const float a1 = dpp_shr1(0.f, g[e]), a2 = dpp_shr2(0.f, g[e]); p1[e] = (t >= 1) ? a1 : s1[e]; p2[e] = (t >= 2) ? a2 : (t == 1 ? s1[e] : s0[e]); }
;                         if (t >= 6) *(f32x4*)(out + O_SFFN + ((size_t)bs * 2 + (t - 6)) * DFF + j0 + 4 * n) = g;
;                     }
;                     const f32x4 gc = bb + w0 * p2 + w1 * p1 + w2 * g;
; #pragma unroll
;                     for (int e = 0; e < 4; ++e) av[e] = silu_e(gc[e]) * uu[e];
;                     if (n == 0) { keep[ai][m].x = cvt_pk_bf16(av[0], av[1]); keep[ai][m].y = cvt_pk_bf16(av[2], av[3]); }
;                     else { u32x4e w; w.x = keep[ai][m].x; w.y = keep[ai][m].y; w.z = cvt_pk_bf16(av[0], av[1]); w.w = cvt_pk_bf16(av[2], av[3]); *(u32x4e*)(ACT + act_off(r, j0)) = w; }
.LBB0_876:
	v_mov_b32_e32 v30, v37
	v_mov_b32_e32 v31, v41
	v_pk_mul_f32 v[30:31], v[80:81], v[30:31]
	v_fma_f32 v32, v75, v43, v79
	v_add_f32_e32 v31, v31, v32
	v_add_f32_e32 v32, v30, v31
	v_mul_f32_e32 v30, 0xbfb8aa3b, v32
	v_exp_f32_e32 v33, v30
	v_mov_b32_e32 v30, v48
	v_mov_b32_e32 v31, v48
	v_pk_mul_f32 v[28:29], v[28:29], v[30:31]
	v_add_f32_e32 v30, 1.0, v33
	v_mov_b32_e32 v37, v40
	v_rcp_f32_e32 v33, v30
	v_pk_mul_f32 v[30:31], v[88:89], v[36:37]
	v_fma_f32 v36, v74, v42, v78
	v_add_f32_e32 v31, v31, v36
	v_add_f32_e32 v36, v30, v31
	v_mul_f32_e32 v30, 0xbfb8aa3b, v36
	v_exp_f32_e32 v30, v30
	v_mul_f32_e32 v31, v32, v33
	v_mul_f32_e32 v29, v29, v31
	v_mov_b32_e32 v31, v39
	v_add_f32_e32 v30, 1.0, v30
	v_rcp_f32_e32 v32, v30
	v_mov_b32_e32 v30, v35
	v_pk_mul_f32 v[30:31], v[108:109], v[30:31]
	v_fma_f32 v33, v73, v45, v77
	v_add_f32_e32 v31, v31, v33
	v_add_f32_e32 v33, v30, v31
	v_mul_f32_e32 v30, 0xbfb8aa3b, v33
	v_mov_b32_e32 v35, v38
	v_exp_f32_e32 v37, v30
	v_pk_mul_f32 v[30:31], v[86:87], v[34:35]
	v_fma_f32 v34, v72, v44, v76
	v_add_f32_e32 v31, v31, v34
	v_add_f32_e32 v30, v30, v31
	v_mul_f32_e32 v31, 0xbfb8aa3b, v30
	v_exp_f32_e32 v31, v31
	v_add_f32_e32 v34, 1.0, v37
	v_rcp_f32_e32 v34, v34
	v_mov_b32_e32 v49, v48
	v_add_f32_e32 v31, 1.0, v31
	v_rcp_f32_e32 v31, v31
	v_pk_mul_f32 v[26:27], v[26:27], v[48:49]
	v_mul_f32_e32 v32, v36, v32
	v_mul_f32_e32 v28, v28, v32
	v_mul_f32_e32 v30, v30, v31
	v_mul_f32_e32 v32, v33, v34
	v_mul_f32_e32 v26, v26, v30
	v_mul_f32_e32 v27, v27, v32
	v_cvt_pk_bf16_f32 v92, v26, v27
	v_lshrrev_b32_e32 v26, 8, v50
	v_mad_i32_i24 v26, v26, s60, v125
	v_cvt_pk_bf16_f32 v93, v28, v29
	v_ashrrev_i32_e32 v27, 31, v26
	ds_read_b32 v40, v150 offset:128
	v_lshlrev_b64 v[26:27], 15, v[26:27]
	v_lshlrev_b32_e32 v28, 7, v142
	v_lshl_add_u64 v[26:27], s[40:41], 0, v[26:27]
	v_and_b32_e32 v28, 0x7f80, v28
	v_mov_b32_e32 v29, v179
	v_lshl_add_u64 v[26:27], v[26:27], 0, v[28:29]
	v_mov_b32_e32 v111, v179
	v_lshl_add_u64 v[26:27], v[26:27], 0, v[110:111]
	global_store_dwordx4 v[26:27], v[90:93], off sc1
	v_add_u32_e32 v42, s74, v113
	s_waitcnt lgkmcnt(0)
	v_pk_mul_f32 v[28:29], v[12:13], v[40:41] op_sel_hi:[1,0]
	v_pk_mul_f32 v[26:27], v[10:11], v[40:41] op_sel_hi:[1,0]
	s_and_b64 vcc, exec, s[16:17]
	s_mov_b64 s[18:19], -1
	s_cbranch_vccnz .LBB0_882
	v_add_u32_e32 v30, 0xffffe000, v42
	v_ashrrev_i32_e32 v30, 3, v30
	v_mov_b32_e32 v32, 0
	v_mov_b32_e32 v33, 0
	v_mov_b32_e32 v34, 0
	v_mov_b32_e32 v35, 0
	v_mov_b32_e32 v36, 0
	v_mov_b32_e32 v37, 0
	v_mov_b32_e32 v38, 0
	v_mov_b32_e32 v39, 0
	s_and_saveexec_b64 s[18:19], s[14:15]
	s_cbranch_execz .LBB0_879
	v_mov_b64_e32 v[32:33], s[36:37]
	v_mad_i64_i32 v[32:33], s[20:21], v30, s53, v[32:33]
	v_lshl_add_u64 v[32:33], v[184:185], 2, v[32:33]
	v_add_co_u32_e32 v36, vcc, 0xa000, v32
	s_nop 1
	v_addc_co_u32_e32 v37, vcc, 0, v33, vcc
	global_load_dwordx4 v[32:35], v[32:33], off offset:16
	s_nop 0
	global_load_dwordx4 v[36:39], v[36:37], off offset:3088

; __device__ __forceinline__ size_t act_off(int r, int j) { return ((size_t)((r >> 8) * (DFF / 64) + (j >> 6)) * 256 + (r & 255)) * 64 + (j & 63); }
;     __device__ __forceinline__ void operator()(const f32x4 (&acc)[2][2][4][2], const Unit& u, int wr, int wc, int fr, int fq) const {
;     ...
;                     const int r = u.pm * BM + ai * HALF + wr * 64 + m * 16 + fr;
;                     const float rsm = RS[16 * m]; const f32x4 g = acc[ai][0][m][n] * rsm, uu = acc[ai][1][m][n] * rsm; f32x4 p1, p2, av;
;                     if (!sample) {
; #pragma unroll
;                         for (int e = 0; e < 4; ++e) { float o1, o2;
;                             if (m == 0) { o1 = bm1[e]; o2 = (fr == 0) ? bm2[e] : bm1[e]; } else { const float gp = acc[ai][0][m > 0 ? m - 1 : 0][n][e] * RS[16 * (m > 0 ? m - 1 : 0)]; o1 = dpp_ror1(gp); o2 = dpp_ror2(gp); }
;                             p1[e] = dpp_shr1(o1, g[e]); p2[e] = dpp_shr2(o2, g[e]); }
;                         if (ai == 0 && wr == 0 && m == 0 && fr < 2 && (u.pm & 7) != 0) {
;                             *(f32x4*)(fix + ((size_t)(72 + u.pm * 2 + fr)) * DFF + j0 + 4 * n) = g; *(f32x4*)(fix + ((size_t)(144 + u.pm * 2 + fr)) * DFF + j0 + 4 * n) = uu; }
;                     } else {
;                         const int t = fr & 7, bs = (r - MP) >> 3; f32x4 s0 = (f32x4){0.f, 0.f, 0.f, 0.f}, s1 = s0;
;                         if (t < 2) { s0 = *(const f32x4*)(st_ffn + ((size_t)bs * 2 + 0) * DFF + j0 + 4 * n); s1 = *(const f32x4*)(st_ffn + ((size_t)bs * 2 + 1) * DFF + j0 + 4 * n); }
; #pragma unroll
;                         for (int e = 0; e < 4; ++e) { const float a1 = dpp_shr1(0.f, g[e]), a2 = dpp_shr2(0.f, g[e]); p1[e] = (t >= 1) ? a1 : s1[e]; p2[e] = (t >= 2) ? a2 : (t == 1 ? s1[e] : s0[e]); }
;                         if (t >= 6) *(f32x4*)(out + O_SFFN + ((size_t)bs * 2 + (t - 6)) * DFF + j0 + 4 * n) = g;
;                     }
;                     const f32x4 gc = bb + w0 * p2 + w1 * p1 + w2 * g;
; #pragma unroll
;                     for (int e = 0; e < 4; ++e) av[e] = silu_e(gc[e]) * uu[e];
;                     if (n == 0) { keep[ai][m].x = cvt_pk_bf16(av[0], av[1]); keep[ai][m].y = cvt_pk_bf16(av[2], av[3]); }
;                     else { u32x4e w; w.x = keep[ai][m].x; w.y = keep[ai][m].y; w.z = cvt_pk_bf16(av[0], av[1]); w.w = cvt_pk_bf16(av[2], av[3]); *(u32x4e*)(ACT + act_off(r, j0)) = w; }
.LBB0_884:
	v_mov_b32_e32 v22, v29
	v_mov_b32_e32 v23, v33
	v_pk_mul_f32 v[22:23], v[80:81], v[22:23]
	v_fma_f32 v24, v75, v35, v79
	v_add_f32_e32 v23, v23, v24
	v_add_f32_e32 v24, v22, v23
	v_mul_f32_e32 v22, 0xbfb8aa3b, v24
	v_exp_f32_e32 v25, v22
	v_mov_b32_e32 v22, v40
	v_mov_b32_e32 v23, v40
	v_pk_mul_f32 v[20:21], v[20:21], v[22:23]
	v_add_f32_e32 v22, 1.0, v25
	v_mov_b32_e32 v29, v32
	v_rcp_f32_e32 v25, v22
	v_pk_mul_f32 v[22:23], v[88:89], v[28:29]
	v_fma_f32 v28, v74, v34, v78
	v_add_f32_e32 v23, v23, v28
	v_add_f32_e32 v28, v22, v23
	v_mul_f32_e32 v22, 0xbfb8aa3b, v28
	v_exp_f32_e32 v22, v22
	v_mul_f32_e32 v23, v24, v25
	v_mul_f32_e32 v21, v21, v23
	v_mov_b32_e32 v23, v31
	v_add_f32_e32 v22, 1.0, v22
	v_rcp_f32_e32 v24, v22
	v_mov_b32_e32 v22, v27
	v_pk_mul_f32 v[22:23], v[108:109], v[22:23]
	v_fma_f32 v25, v73, v37, v77
	v_add_f32_e32 v23, v23, v25
	v_add_f32_e32 v25, v22, v23
	v_mul_f32_e32 v22, 0xbfb8aa3b, v25
	v_mov_b32_e32 v27, v30
	v_exp_f32_e32 v29, v22
	v_pk_mul_f32 v[22:23], v[86:87], v[26:27]
	v_fma_f32 v26, v72, v36, v76
	v_add_f32_e32 v23, v23, v26
	v_add_f32_e32 v22, v22, v23
	v_mul_f32_e32 v23, 0xbfb8aa3b, v22
	v_exp_f32_e32 v23, v23
	v_add_f32_e32 v26, 1.0, v29
	v_rcp_f32_e32 v26, v26
	v_mov_b32_e32 v41, v40
	v_add_f32_e32 v23, 1.0, v23
	v_rcp_f32_e32 v23, v23
	v_pk_mul_f32 v[18:19], v[18:19], v[40:41]
	v_mul_f32_e32 v24, v28, v24
	v_mul_f32_e32 v20, v20, v24
	v_mul_f32_e32 v22, v22, v23
	v_mul_f32_e32 v24, v25, v26
	v_mul_f32_e32 v18, v18, v22
	v_mul_f32_e32 v19, v19, v24
	v_cvt_pk_bf16_f32 v84, v18, v19
	v_lshrrev_b32_e32 v18, 8, v42
	v_cvt_pk_bf16_f32 v85, v20, v21
	v_mad_i32_i24 v18, v18, s60, v125
	ds_read_b32 v28, v150 offset:192
	v_ashrrev_i32_e32 v19, 31, v18
	v_lshlrev_b64 v[18:19], 15, v[18:19]
	v_lshlrev_b32_e32 v20, 7, v113
	v_lshl_add_u64 v[18:19], s[40:41], 0, v[18:19]
	v_and_b32_e32 v20, 0x7f80, v20
	v_mov_b32_e32 v21, v179
	v_lshl_add_u64 v[18:19], v[18:19], 0, v[20:21]
	v_mov_b32_e32 v111, v179
	v_lshl_add_u64 v[18:19], v[18:19], 0, v[110:111]
	v_add_u32_e32 v30, s74, v112
	s_waitcnt lgkmcnt(0)
	v_pk_mul_f32 v[16:17], v[16:17], v[28:29] op_sel_hi:[1,0]
	v_pk_mul_f32 v[14:15], v[14:15], v[28:29] op_sel_hi:[1,0]
	s_and_b64 vcc, exec, s[16:17]
	s_mov_b64 s[16:17], -1
	global_store_dwordx4 v[18:19], v[82:85], off sc1
	s_cbranch_vccnz .LBB0_890
	v_add_u32_e32 v18, 0xffffe000, v30
	v_ashrrev_i32_e32 v18, 3, v18
	v_mov_b32_e32 v20, 0
	v_mov_b32_e32 v21, 0
	v_mov_b32_e32 v22, 0
	v_mov_b32_e32 v23, 0
	v_mov_b32_e32 v24, 0
	v_mov_b32_e32 v25, 0
	v_mov_b32_e32 v26, 0
	v_mov_b32_e32 v27, 0
	s_and_saveexec_b64 s[16:17], s[14:15]
	s_cbranch_execz .LBB0_887
	v_mov_b64_e32 v[20:21], s[36:37]
	v_mad_i64_i32 v[20:21], s[14:15], v18, s53, v[20:21]
	v_lshl_add_u64 v[20:21], v[184:185], 2, v[20:21]
	v_add_co_u32_e32 v24, vcc, 0xa000, v20
	s_nop 1
	v_addc_co_u32_e32 v25, vcc, 0, v21, vcc
	global_load_dwordx4 v[20:23], v[20:21], off offset:16
	s_nop 0
	global_load_dwordx4 v[24:27], v[24:25], off offset:3088

; __device__ __forceinline__ size_t act_off(int r, int j) { return ((size_t)((r >> 8) * (DFF / 64) + (j >> 6)) * 256 + (r & 255)) * 64 + (j & 63); }
;     __device__ __forceinline__ void operator()(const f32x4 (&acc)[2][2][4][2], const Unit& u, int wr, int wc, int fr, int fq) const {
;     ...
;                     const int r = u.pm * BM + ai * HALF + wr * 64 + m * 16 + fr;
;                     const float rsm = RS[16 * m]; const f32x4 g = acc[ai][0][m][n] * rsm, uu = acc[ai][1][m][n] * rsm; f32x4 p1, p2, av;
;                     if (!sample) {
; #pragma unroll
;                         for (int e = 0; e < 4; ++e) { float o1, o2;
;                             if (m == 0) { o1 = bm1[e]; o2 = (fr == 0) ? bm2[e] : bm1[e]; } else { const float gp = acc[ai][0][m > 0 ? m - 1 : 0][n][e] * RS[16 * (m > 0 ? m - 1 : 0)]; o1 = dpp_ror1(gp); o2 = dpp_ror2(gp); }
;                             p1[e] = dpp_shr1(o1, g[e]); p2[e] = dpp_shr2(o2, g[e]); }
;                         if (ai == 0 && wr == 0 && m == 0 && fr < 2 && (u.pm & 7) != 0) {
;                             *(f32x4*)(fix + ((size_t)(72 + u.pm * 2 + fr)) * DFF + j0 + 4 * n) = g; *(f32x4*)(fix + ((size_t)(144 + u.pm * 2 + fr)) * DFF + j0 + 4 * n) = uu; }
;                     } else {
;                         const int t = fr & 7, bs = (r - MP) >> 3; f32x4 s0 = (f32x4){0.f, 0.f, 0.f, 0.f}, s1 = s0;
;                         if (t < 2) { s0 = *(const f32x4*)(st_ffn + ((size_t)bs * 2 + 0) * DFF + j0 + 4 * n); s1 = *(const f32x4*)(st_ffn + ((size_t)bs * 2 + 1) * DFF + j0 + 4 * n); }
; #pragma unroll
;                         for (int e = 0; e < 4; ++e) { const float a1 = dpp_shr1(0.f, g[e]), a2 = dpp_shr2(0.f, g[e]); p1[e] = (t >= 1) ? a1 : s1[e]; p2[e] = (t >= 2) ? a2 : (t == 1 ? s1[e] : s0[e]); }
;                         if (t >= 6) *(f32x4*)(out + O_SFFN + ((size_t)bs * 2 + (t - 6)) * DFF + j0 + 4 * n) = g;
;                     }
;                     const f32x4 gc = bb + w0 * p2 + w1 * p1 + w2 * g;
; #pragma unroll
;                     for (int e = 0; e < 4; ++e) av[e] = silu_e(gc[e]) * uu[e];
;                     if (n == 0) { keep[ai][m].x = cvt_pk_bf16(av[0], av[1]); keep[ai][m].y = cvt_pk_bf16(av[2], av[3]); }
;                     else { u32x4e w; w.x = keep[ai][m].x; w.y = keep[ai][m].y; w.z = cvt_pk_bf16(av[0], av[1]); w.w = cvt_pk_bf16(av[2], av[3]); *(u32x4e*)(ACT + act_off(r, j0)) = w; }
.LBB0_892:
	v_mov_b32_e32 v10, v17
	v_mov_b32_e32 v11, v21
	v_pk_mul_f32 v[10:11], v[80:81], v[10:11]
	v_fma_f32 v12, v75, v23, v79
	v_add_f32_e32 v11, v11, v12
	v_add_f32_e32 v12, v10, v11
	v_mul_f32_e32 v10, 0xbfb8aa3b, v12
	v_exp_f32_e32 v13, v10
	v_mov_b32_e32 v10, v28
	v_mov_b32_e32 v11, v28
	v_pk_mul_f32 v[8:9], v[8:9], v[10:11]
	v_add_f32_e32 v10, 1.0, v13
	v_mov_b32_e32 v17, v20
	v_rcp_f32_e32 v13, v10
	v_pk_mul_f32 v[10:11], v[88:89], v[16:17]
	v_fma_f32 v16, v74, v22, v78
	v_add_f32_e32 v11, v11, v16
	v_add_f32_e32 v16, v10, v11
	v_mul_f32_e32 v10, 0xbfb8aa3b, v16
	v_exp_f32_e32 v10, v10
	v_mul_f32_e32 v11, v12, v13
	v_mul_f32_e32 v9, v9, v11
	v_mov_b32_e32 v11, v19
	v_add_f32_e32 v10, 1.0, v10
	v_rcp_f32_e32 v12, v10
	v_mov_b32_e32 v10, v15
	v_pk_mul_f32 v[10:11], v[108:109], v[10:11]
	v_fma_f32 v13, v73, v25, v77
	v_add_f32_e32 v11, v11, v13
	v_add_f32_e32 v13, v10, v11
	v_mul_f32_e32 v10, 0xbfb8aa3b, v13
	v_mov_b32_e32 v15, v18
	v_exp_f32_e32 v17, v10
	v_pk_mul_f32 v[10:11], v[86:87], v[14:15]
	v_fmac_f32_e32 v76, v72, v24
	v_add_f32_e32 v11, v11, v76
	v_add_f32_e32 v10, v10, v11
	v_mul_f32_e32 v11, 0xbfb8aa3b, v10
	v_exp_f32_e32 v11, v11
	v_add_f32_e32 v14, 1.0, v17
	v_rcp_f32_e32 v14, v14
	v_mov_b32_e32 v29, v28
	v_add_f32_e32 v11, 1.0, v11
	v_rcp_f32_e32 v11, v11
	v_pk_mul_f32 v[6:7], v[6:7], v[28:29]
	v_mul_f32_e32 v12, v16, v12
	v_mul_f32_e32 v8, v8, v12
	v_mul_f32_e32 v10, v10, v11
	v_mul_f32_e32 v12, v13, v14
	v_mul_f32_e32 v6, v6, v10
	v_mul_f32_e32 v7, v7, v12
	v_cvt_pk_bf16_f32 v72, v6, v7
	v_lshrrev_b32_e32 v6, 8, v30
	v_mad_i32_i24 v6, v6, s60, v125
	v_ashrrev_i32_e32 v7, 31, v6
	v_cvt_pk_bf16_f32 v73, v8, v9
	v_lshlrev_b64 v[6:7], 15, v[6:7]
	v_lshlrev_b32_e32 v8, 7, v112
	v_lshl_add_u64 v[6:7], s[40:41], 0, v[6:7]
	v_and_b32_e32 v178, 0x7f80, v8
	v_lshl_add_u64 v[6:7], v[6:7], 0, v[178:179]
	v_mov_b32_e32 v111, v179
	v_lshl_add_u64 v[6:7], v[6:7], 0, v[110:111]
	s_andn2_b64 vcc, exec, s[68:69]
	s_mov_b64 s[6:7], -1
	global_store_dwordx4 v[6:7], v[70:73], off sc1
	s_cbranch_vccnz .LBB0_705
	s_andn2_b64 vcc, exec, s[38:39]
	s_cbranch_vccnz .LBB0_704
	s_barrier
	s_branch .LBB0_704
